# exec=0 dry-run instruction prefetch on P1 generic + V^T epilogue regions (waves 1-7 each pre-fetch 1/8 of the cold code, then all run it warm); code otherwise unchanged
# speedup vs baseline: 1.0654x; 1.0249x over previous
; __device__ __forceinline__ unsigned f2bf(float f) { unsigned u = __float_as_uint(f); return (u + 0x7fffu + ((u >> 16) & 1u)) >> 16; }
;     __device__ __forceinline__ void operator()(const f32x4 (&acc)[2][2][4][2], const pg8::Unit& u, int wr, int wc, int fr, int fq) const {
;     ...
;             if (seg == 2) {
; #pragma unroll
;                 for (int ai = 0; ai < 2; ++ai)
; #pragma unroll
;                     for (int m = 0; m < 4; ++m) {
;                         const int row = row0 + ai * 128 + m * 16, bb = row >> 13, ss = row & 8191;
; #pragma unroll
;                         for (int bj = 0; bj < 2; ++bj) {
;                             const int col = col0 + bj * 128;
;                             bf16_t* p = sbv + ((size_t)(bb * 1024 + col)) * 8192 + ss;
;                             const f32x4 a = acc[ai][bj][m][0], b = acc[ai][bj][m][1];
; #pragma unroll
;                             for (int j = 0; j < 4; ++j) { p[(size_t)j * 8192] = (bf16_t)f2bf(a[j]); p[(size_t)(4 + j) * 8192] = (bf16_t)f2bf(b[j]); }
;                         }
;                     }
;                 return;
.LBB0_106:
	s_and_b64 vcc, exec, s[38:39]
	s_cbranch_vccz .LBB0_146
	v_readfirstlane_b32 s98, v200
	s_nop 0
	s_lshr_b32 s98, s98, 6
	s_cmp_eq_u32 s98, 0
	s_cbranch_scc1 .Ldry_p1vt_real
	s_mov_b64 exec, 0
	s_cmp_eq_u32 s98, 1
	s_cbranch_scc1 .Ldry_p1vt_c1
	s_cmp_eq_u32 s98, 2
	s_cbranch_scc1 .Ldry_p1vt_c2
	s_cmp_eq_u32 s98, 3
	s_cbranch_scc1 .Ldry_p1vt_c3
	s_cmp_eq_u32 s98, 4
	s_cbranch_scc1 .Ldry_p1vt_c4
	s_cmp_eq_u32 s98, 5
	s_cbranch_scc1 .Ldry_p1vt_c5
	s_cmp_eq_u32 s98, 6
	s_cbranch_scc1 .Ldry_p1vt_c6
	s_branch .Ldry_p1vt_c7
.Ldry_p1vt_real:
	s_mov_b64 exec, -1
	s_ashr_i32 s3, s27, 3
	s_and_b32 s3, s3, 0xfffffc00
	v_and_b32_e32 v129, 0x1fcf, v154
	v_or_b32_e32 v128, s3, v178
	v_lshlrev_b32_e32 v144, 1, v129
	v_ashrrev_i32_e32 v129, 31, v128
	v_lshl_add_u64 v[130:131], s[8:9], 0, v[144:145]
	v_lshlrev_b64 v[132:133], 14, v[128:129]
	v_bfe_u32 v129, v124, 16, 1
	v_lshl_add_u64 v[132:133], v[130:131], 0, v[132:133]
	v_add3_u32 v124, v124, v129, s21
	global_store_short_d16_hi v[132:133], v124, off
	v_bfe_u32 v124, v120, 16, 1
	v_add_co_u32_e32 v134, vcc, s85, v132
	v_add3_u32 v120, v120, v124, s21
	s_nop 0
	v_addc_co_u32_e32 v135, vcc, 0, v133, vcc
	global_store_short_d16_hi v[134:135], v120, off
	v_bfe_u32 v120, v125, 16, 1
	v_add_co_u32_e32 v124, vcc, s87, v132
	v_add3_u32 v120, v125, v120, s21
	s_nop 0
	v_addc_co_u32_e32 v125, vcc, 0, v133, vcc
	global_store_short_d16_hi v[124:125], v120, off
	v_bfe_u32 v120, v121, 16, 1
	v_add3_u32 v129, v121, v120, s21
	v_add_co_u32_e32 v120, vcc, s86, v132
	v_or_b32_e32 v128, 0x80, v128
	s_nop 0
	v_addc_co_u32_e32 v121, vcc, 0, v133, vcc
	global_store_short_d16_hi v[120:121], v129, off
	v_bfe_u32 v129, v126, 16, 1
	v_add_co_u32_e32 v156, vcc, s92, v132
	v_add3_u32 v126, v126, v129, s21
	s_nop 0
	v_addc_co_u32_e32 v157, vcc, 0, v133, vcc
	global_store_short_d16_hi v[156:157], v126, off
	v_bfe_u32 v126, v122, 16, 1
	v_add_co_u32_e32 v158, vcc, s91, v132
	v_add3_u32 v122, v122, v126, s21
	s_nop 0
	v_addc_co_u32_e32 v159, vcc, 0, v133, vcc
	global_store_short_d16_hi v[158:159], v122, off
	v_bfe_u32 v122, v127, 16, 1
	v_add_co_u32_e32 v126, vcc, s11, v132
	v_add3_u32 v122, v127, v122, s21
	s_nop 0
	v_addc_co_u32_e32 v127, vcc, 0, v133, vcc
	global_store_short_d16_hi v[126:127], v122, off
	v_bfe_u32 v122, v123, 16, 1
	v_add3_u32 v129, v123, v122, s21
	v_add_co_u32_e32 v122, vcc, s93, v132
	s_movk_i32 s3, 0xfc00
	s_nop 0
	v_addc_co_u32_e32 v123, vcc, 0, v133, vcc
	global_store_short_d16_hi v[122:123], v129, off
	v_ashrrev_i32_e32 v129, 31, v128
	v_lshlrev_b64 v[128:129], 14, v[128:129]
	v_lshl_add_u64 v[128:129], v[130:131], 0, v[128:129]
	v_bfe_u32 v130, v116, 16, 1
	v_add3_u32 v116, v116, v130, s21
	global_store_short_d16_hi v[128:129], v116, off
	s_cbranch_execz .Ldry_p1vt_real
.Ldry_p1vt_c1:
	v_bfe_u32 v116, v108, 16, 1
	v_add_co_u32_e32 v130, vcc, s85, v128
	v_add3_u32 v108, v108, v116, s21
	s_nop 0
	v_addc_co_u32_e32 v131, vcc, 0, v129, vcc
	global_store_short_d16_hi v[130:131], v108, off
	v_bfe_u32 v108, v117, 16, 1
	v_add_co_u32_e32 v116, vcc, s87, v128
	v_add3_u32 v108, v117, v108, s21
	s_nop 0
	v_addc_co_u32_e32 v117, vcc, 0, v129, vcc
	global_store_short_d16_hi v[116:117], v108, off
	v_bfe_u32 v108, v109, 16, 1
	v_add3_u32 v144, v109, v108, s21
	v_add_co_u32_e32 v108, vcc, s86, v128
	s_nop 1
	v_addc_co_u32_e32 v109, vcc, 0, v129, vcc
	global_store_short_d16_hi v[108:109], v144, off
	v_bfe_u32 v144, v118, 16, 1
	v_add_co_u32_e32 v160, vcc, s92, v128
	v_add3_u32 v118, v118, v144, s21
	s_nop 0
	v_addc_co_u32_e32 v161, vcc, 0, v129, vcc
	global_store_short_d16_hi v[160:161], v118, off
	v_bfe_u32 v118, v110, 16, 1
	v_add_co_u32_e32 v162, vcc, s91, v128
	v_add3_u32 v110, v110, v118, s21
	s_nop 0
	v_addc_co_u32_e32 v163, vcc, 0, v129, vcc
	global_store_short_d16_hi v[162:163], v110, off
	v_bfe_u32 v110, v119, 16, 1
	v_add_co_u32_e32 v118, vcc, s11, v128
	v_add3_u32 v110, v119, v110, s21
	s_nop 0
	v_addc_co_u32_e32 v119, vcc, 0, v129, vcc
	global_store_short_d16_hi v[118:119], v110, off
	v_bfe_u32 v110, v111, 16, 1
	v_add3_u32 v144, v111, v110, s21
	v_add_co_u32_e32 v110, vcc, s93, v128
	s_nop 1
	v_addc_co_u32_e32 v111, vcc, 0, v129, vcc
	global_store_short_d16_hi v[110:111], v144, off
	v_bfe_u32 v144, v112, 16, 1
	v_add3_u32 v112, v112, v144, s21
	global_store_short_d16_hi v[132:133], v112, off offset:32
	v_bfe_u32 v112, v104, 16, 1
	v_add3_u32 v104, v104, v112, s21
	global_store_short_d16_hi v[134:135], v104, off offset:32
	v_bfe_u32 v104, v113, 16, 1
	v_add3_u32 v104, v113, v104, s21
	global_store_short_d16_hi v[124:125], v104, off offset:32
	v_bfe_u32 v104, v105, 16, 1
	v_add3_u32 v104, v105, v104, s21
	global_store_short_d16_hi v[120:121], v104, off offset:32
	v_bfe_u32 v104, v114, 16, 1
	v_add3_u32 v104, v114, v104, s21
	global_store_short_d16_hi v[156:157], v104, off offset:32
	v_bfe_u32 v104, v106, 16, 1
	v_add3_u32 v104, v106, v104, s21
	global_store_short_d16_hi v[158:159], v104, off offset:32
	v_bfe_u32 v104, v115, 16, 1
	v_add3_u32 v104, v115, v104, s21
	s_cbranch_execz .Ldry_p1vt_real
; __device__ __forceinline__ unsigned f2bf(float f) { unsigned u = __float_as_uint(f); return (u + 0x7fffu + ((u >> 16) & 1u)) >> 16; }
;     __device__ __forceinline__ void operator()(const f32x4 (&acc)[2][2][4][2], const pg8::Unit& u, int wr, int wc, int fr, int fq) const {
;     ...
;             if (seg == 2) {
; #pragma unroll
;                 for (int ai = 0; ai < 2; ++ai)
; #pragma unroll
;                     for (int m = 0; m < 4; ++m) {
;                         const int row = row0 + ai * 128 + m * 16, bb = row >> 13, ss = row & 8191;
; #pragma unroll
;                         for (int bj = 0; bj < 2; ++bj) {
;                             const int col = col0 + bj * 128;
;                             bf16_t* p = sbv + ((size_t)(bb * 1024 + col)) * 8192 + ss;
;                             const f32x4 a = acc[ai][bj][m][0], b = acc[ai][bj][m][1];
; #pragma unroll
;                             for (int j = 0; j < 4; ++j) { p[(size_t)j * 8192] = (bf16_t)f2bf(a[j]); p[(size_t)(4 + j) * 8192] = (bf16_t)f2bf(b[j]); }
;                         }
;                     }
;                 return;
.Ldry_p1vt_c2:
	global_store_short_d16_hi v[126:127], v104, off offset:32
	v_bfe_u32 v104, v107, 16, 1
	v_add3_u32 v104, v107, v104, s21
	global_store_short_d16_hi v[122:123], v104, off offset:32
	v_bfe_u32 v104, v96, 16, 1
	v_add3_u32 v96, v96, v104, s21
	global_store_short_d16_hi v[128:129], v96, off offset:32
	v_bfe_u32 v96, v88, 16, 1
	v_add3_u32 v88, v88, v96, s21
	global_store_short_d16_hi v[130:131], v88, off offset:32
	v_bfe_u32 v88, v97, 16, 1
	v_add3_u32 v88, v97, v88, s21
	global_store_short_d16_hi v[116:117], v88, off offset:32
	v_bfe_u32 v88, v89, 16, 1
	v_add3_u32 v88, v89, v88, s21
	global_store_short_d16_hi v[108:109], v88, off offset:32
	v_bfe_u32 v88, v98, 16, 1
	v_add3_u32 v88, v98, v88, s21
	global_store_short_d16_hi v[160:161], v88, off offset:32
	v_bfe_u32 v88, v90, 16, 1
	v_add3_u32 v88, v90, v88, s21
	global_store_short_d16_hi v[162:163], v88, off offset:32
	v_bfe_u32 v88, v99, 16, 1
	v_add3_u32 v88, v99, v88, s21
	global_store_short_d16_hi v[118:119], v88, off offset:32
	v_bfe_u32 v88, v91, 16, 1
	v_add3_u32 v88, v91, v88, s21
	global_store_short_d16_hi v[110:111], v88, off offset:32
	v_bfe_u32 v88, v100, 16, 1
	v_add3_u32 v88, v100, v88, s21
	global_store_short_d16_hi v[132:133], v88, off offset:64
	v_bfe_u32 v88, v92, 16, 1
	v_add3_u32 v88, v92, v88, s21
	global_store_short_d16_hi v[134:135], v88, off offset:64
	v_bfe_u32 v88, v101, 16, 1
	v_add3_u32 v88, v101, v88, s21
	global_store_short_d16_hi v[124:125], v88, off offset:64
	v_bfe_u32 v88, v93, 16, 1
	v_add3_u32 v88, v93, v88, s21
	global_store_short_d16_hi v[120:121], v88, off offset:64
	v_bfe_u32 v88, v102, 16, 1
	v_add3_u32 v88, v102, v88, s21
	global_store_short_d16_hi v[156:157], v88, off offset:64
	v_bfe_u32 v88, v94, 16, 1
	v_add3_u32 v88, v94, v88, s21
	global_store_short_d16_hi v[158:159], v88, off offset:64
	v_bfe_u32 v88, v103, 16, 1
	v_add3_u32 v88, v103, v88, s21
	global_store_short_d16_hi v[126:127], v88, off offset:64
	v_bfe_u32 v88, v95, 16, 1
	v_add3_u32 v88, v95, v88, s21
	global_store_short_d16_hi v[122:123], v88, off offset:64
	v_bfe_u32 v88, v80, 16, 1
	v_add3_u32 v80, v80, v88, s21
	global_store_short_d16_hi v[128:129], v80, off offset:64
	v_bfe_u32 v80, v72, 16, 1
	v_add3_u32 v72, v72, v80, s21
	global_store_short_d16_hi v[130:131], v72, off offset:64
	v_bfe_u32 v72, v81, 16, 1
	v_add3_u32 v72, v81, v72, s21
	global_store_short_d16_hi v[116:117], v72, off offset:64
	v_bfe_u32 v72, v73, 16, 1
	s_cbranch_execz .Ldry_p1vt_real
.Ldry_p1vt_c3:
	v_add3_u32 v72, v73, v72, s21
	global_store_short_d16_hi v[108:109], v72, off offset:64
	v_bfe_u32 v72, v82, 16, 1
	v_add3_u32 v72, v82, v72, s21
	global_store_short_d16_hi v[160:161], v72, off offset:64
	v_bfe_u32 v72, v74, 16, 1
	v_add3_u32 v72, v74, v72, s21
	global_store_short_d16_hi v[162:163], v72, off offset:64
	v_bfe_u32 v72, v83, 16, 1
	v_add3_u32 v72, v83, v72, s21
	global_store_short_d16_hi v[118:119], v72, off offset:64
	v_bfe_u32 v72, v75, 16, 1
	v_add3_u32 v72, v75, v72, s21
	global_store_short_d16_hi v[110:111], v72, off offset:64
	v_bfe_u32 v72, v84, 16, 1
	v_add3_u32 v72, v84, v72, s21
	global_store_short_d16_hi v[132:133], v72, off offset:96
	v_bfe_u32 v72, v76, 16, 1
	v_add3_u32 v72, v76, v72, s21
	global_store_short_d16_hi v[134:135], v72, off offset:96
	v_bfe_u32 v72, v85, 16, 1
	v_add3_u32 v72, v85, v72, s21
	global_store_short_d16_hi v[124:125], v72, off offset:96
	v_bfe_u32 v72, v77, 16, 1
	v_add3_u32 v72, v77, v72, s21
	global_store_short_d16_hi v[120:121], v72, off offset:96
	v_bfe_u32 v72, v86, 16, 1
	v_add3_u32 v72, v86, v72, s21
	global_store_short_d16_hi v[156:157], v72, off offset:96
	v_bfe_u32 v72, v78, 16, 1
	v_add3_u32 v72, v78, v72, s21
	global_store_short_d16_hi v[158:159], v72, off offset:96
	v_bfe_u32 v72, v87, 16, 1
	v_add3_u32 v72, v87, v72, s21
	global_store_short_d16_hi v[126:127], v72, off offset:96
	v_bfe_u32 v72, v79, 16, 1
	v_add3_u32 v72, v79, v72, s21
	global_store_short_d16_hi v[122:123], v72, off offset:96
	v_bfe_u32 v72, v68, 16, 1
	v_add3_u32 v68, v68, v72, s21
	global_store_short_d16_hi v[128:129], v68, off offset:96
	v_bfe_u32 v68, v64, 16, 1
	v_add3_u32 v64, v64, v68, s21
	global_store_short_d16_hi v[130:131], v64, off offset:96
	v_bfe_u32 v64, v69, 16, 1
	v_add3_u32 v64, v69, v64, s21
	global_store_short_d16_hi v[116:117], v64, off offset:96
	v_bfe_u32 v64, v65, 16, 1
	v_add3_u32 v64, v65, v64, s21
	global_store_short_d16_hi v[108:109], v64, off offset:96
	v_bfe_u32 v64, v70, 16, 1
	v_add3_u32 v64, v70, v64, s21
	global_store_short_d16_hi v[160:161], v64, off offset:96
	v_bfe_u32 v64, v66, 16, 1
	v_add3_u32 v64, v66, v64, s21
	global_store_short_d16_hi v[162:163], v64, off offset:96
	v_bfe_u32 v64, v71, 16, 1
	v_add3_u32 v64, v71, v64, s21
	global_store_short_d16_hi v[118:119], v64, off offset:96
	v_bfe_u32 v64, v67, 16, 1
	v_add3_u32 v64, v67, v64, s21
	global_store_short_d16_hi v[110:111], v64, off offset:96
	s_cbranch_execz .Ldry_p1vt_real
; __device__ __forceinline__ unsigned f2bf(float f) { unsigned u = __float_as_uint(f); return (u + 0x7fffu + ((u >> 16) & 1u)) >> 16; }
;     __device__ __forceinline__ void operator()(const f32x4 (&acc)[2][2][4][2], const pg8::Unit& u, int wr, int wc, int fr, int fq) const {
;     ...
;             if (seg == 2) {
; #pragma unroll
;                 for (int ai = 0; ai < 2; ++ai)
; #pragma unroll
;                     for (int m = 0; m < 4; ++m) {
;                         const int row = row0 + ai * 128 + m * 16, bb = row >> 13, ss = row & 8191;
; #pragma unroll
;                         for (int bj = 0; bj < 2; ++bj) {
;                             const int col = col0 + bj * 128;
;                             bf16_t* p = sbv + ((size_t)(bb * 1024 + col)) * 8192 + ss;
;                             const f32x4 a = acc[ai][bj][m][0], b = acc[ai][bj][m][1];
; #pragma unroll
;                             for (int j = 0; j < 4; ++j) { p[(size_t)j * 8192] = (bf16_t)f2bf(a[j]); p[(size_t)(4 + j) * 8192] = (bf16_t)f2bf(b[j]); }
;                         }
;                     }
;                 return;
.Ldry_p1vt_c4:
	v_add_u32_e32 v64, 0x80, v154
	v_and_b32_e32 v65, 0x1fcf, v64
	v_ashrrev_i32_e32 v64, 3, v64
	v_and_or_b32 v64, v64, s3, v178
	v_lshlrev_b32_e32 v144, 1, v65
	v_ashrrev_i32_e32 v65, 31, v64
	v_lshl_add_u64 v[66:67], s[8:9], 0, v[144:145]
	v_lshlrev_b64 v[68:69], 14, v[64:65]
	v_bfe_u32 v65, v60, 16, 1
	v_lshl_add_u64 v[68:69], v[66:67], 0, v[68:69]
	v_add3_u32 v60, v60, v65, s21
	global_store_short_d16_hi v[68:69], v60, off
	v_bfe_u32 v60, v56, 16, 1
	v_add_co_u32_e32 v70, vcc, s85, v68
	v_add3_u32 v56, v56, v60, s21
	s_nop 0
	v_addc_co_u32_e32 v71, vcc, 0, v69, vcc
	global_store_short_d16_hi v[70:71], v56, off
	v_bfe_u32 v56, v61, 16, 1
	v_add_co_u32_e32 v60, vcc, s87, v68
	v_add3_u32 v56, v61, v56, s21
	s_nop 0
	v_addc_co_u32_e32 v61, vcc, 0, v69, vcc
	global_store_short_d16_hi v[60:61], v56, off
	v_bfe_u32 v56, v57, 16, 1
	v_add3_u32 v65, v57, v56, s21
	v_add_co_u32_e32 v56, vcc, s86, v68
	v_or_b32_e32 v64, 0x80, v64
	s_nop 0
	v_addc_co_u32_e32 v57, vcc, 0, v69, vcc
	global_store_short_d16_hi v[56:57], v65, off
	v_bfe_u32 v65, v62, 16, 1
	v_add_co_u32_e32 v72, vcc, s92, v68
	v_add3_u32 v62, v62, v65, s21
	s_nop 0
	v_addc_co_u32_e32 v73, vcc, 0, v69, vcc
	global_store_short_d16_hi v[72:73], v62, off
	v_bfe_u32 v62, v58, 16, 1
	v_add_co_u32_e32 v74, vcc, s91, v68
	v_add3_u32 v58, v58, v62, s21
	s_nop 0
	v_addc_co_u32_e32 v75, vcc, 0, v69, vcc
	global_store_short_d16_hi v[74:75], v58, off
	v_bfe_u32 v58, v63, 16, 1
	v_add_co_u32_e32 v62, vcc, s11, v68
	v_add3_u32 v58, v63, v58, s21
	s_nop 0
	v_addc_co_u32_e32 v63, vcc, 0, v69, vcc
	global_store_short_d16_hi v[62:63], v58, off
	v_bfe_u32 v58, v59, 16, 1
	v_add3_u32 v65, v59, v58, s21
	v_add_co_u32_e32 v58, vcc, s93, v68
	s_nop 1
	v_addc_co_u32_e32 v59, vcc, 0, v69, vcc
	global_store_short_d16_hi v[58:59], v65, off
	v_ashrrev_i32_e32 v65, 31, v64
	v_lshlrev_b64 v[64:65], 14, v[64:65]
	v_lshl_add_u64 v[64:65], v[66:67], 0, v[64:65]
	v_bfe_u32 v66, v52, 16, 1
	v_add3_u32 v52, v52, v66, s21
	global_store_short_d16_hi v[64:65], v52, off
	v_bfe_u32 v52, v44, 16, 1
	s_cbranch_execz .Ldry_p1vt_real
.Ldry_p1vt_c5:
	v_add_co_u32_e32 v66, vcc, s85, v64
	v_add3_u32 v44, v44, v52, s21
	s_nop 0
	v_addc_co_u32_e32 v67, vcc, 0, v65, vcc
	global_store_short_d16_hi v[66:67], v44, off
	v_bfe_u32 v44, v53, 16, 1
	v_add_co_u32_e32 v52, vcc, s87, v64
	v_add3_u32 v44, v53, v44, s21
	s_nop 0
	v_addc_co_u32_e32 v53, vcc, 0, v65, vcc
	global_store_short_d16_hi v[52:53], v44, off
	v_bfe_u32 v44, v45, 16, 1
	v_add3_u32 v76, v45, v44, s21
	v_add_co_u32_e32 v44, vcc, s86, v64
	s_nop 1
	v_addc_co_u32_e32 v45, vcc, 0, v65, vcc
	global_store_short_d16_hi v[44:45], v76, off
	v_bfe_u32 v76, v54, 16, 1
	v_add3_u32 v54, v54, v76, s21
	v_add_co_u32_e32 v76, vcc, s92, v64
	s_nop 1
	v_addc_co_u32_e32 v77, vcc, 0, v65, vcc
	global_store_short_d16_hi v[76:77], v54, off
	v_bfe_u32 v54, v46, 16, 1
	v_add_co_u32_e32 v78, vcc, s91, v64
	v_add3_u32 v46, v46, v54, s21
	s_nop 0
	v_addc_co_u32_e32 v79, vcc, 0, v65, vcc
	global_store_short_d16_hi v[78:79], v46, off
	v_bfe_u32 v46, v55, 16, 1
	v_add_co_u32_e32 v54, vcc, s11, v64
	v_add3_u32 v46, v55, v46, s21
	s_nop 0
	v_addc_co_u32_e32 v55, vcc, 0, v65, vcc
	global_store_short_d16_hi v[54:55], v46, off
	v_bfe_u32 v46, v47, 16, 1
	v_add3_u32 v80, v47, v46, s21
	v_add_co_u32_e32 v46, vcc, s93, v64
	s_nop 1
	v_addc_co_u32_e32 v47, vcc, 0, v65, vcc
	global_store_short_d16_hi v[46:47], v80, off
	v_bfe_u32 v80, v48, 16, 1
	v_add3_u32 v48, v48, v80, s21
	global_store_short_d16_hi v[68:69], v48, off offset:32
	v_bfe_u32 v48, v40, 16, 1
	v_add3_u32 v40, v40, v48, s21
	global_store_short_d16_hi v[70:71], v40, off offset:32
	v_bfe_u32 v40, v49, 16, 1
	v_add3_u32 v40, v49, v40, s21
	global_store_short_d16_hi v[60:61], v40, off offset:32
	v_bfe_u32 v40, v41, 16, 1
	v_add3_u32 v40, v41, v40, s21
	global_store_short_d16_hi v[56:57], v40, off offset:32
	v_bfe_u32 v40, v50, 16, 1
	v_add3_u32 v40, v50, v40, s21
	global_store_short_d16_hi v[72:73], v40, off offset:32
	v_bfe_u32 v40, v42, 16, 1
	v_add3_u32 v40, v42, v40, s21
	global_store_short_d16_hi v[74:75], v40, off offset:32
	v_bfe_u32 v40, v51, 16, 1
	v_add3_u32 v40, v51, v40, s21
	global_store_short_d16_hi v[62:63], v40, off offset:32
	s_cbranch_execz .Ldry_p1vt_real
; __device__ __forceinline__ unsigned f2bf(float f) { unsigned u = __float_as_uint(f); return (u + 0x7fffu + ((u >> 16) & 1u)) >> 16; }
; template <class Epi, class Sched, bool ALIGN_EPI = false, bool SP2 = false>
; __device__ __forceinline__ void gemm_phase(LAS unsigned char* lds, const Gemm g, const Sched& S, const Epi& E) {
;     ...
;         if (!has_next) break;
;     __device__ __forceinline__ void operator()(const f32x4 (&acc)[2][2][4][2], const pg8::Unit& u, int wr, int wc, int fr, int fq) const {
;     ...
;             if (seg == 2) {
; #pragma unroll
;                 for (int ai = 0; ai < 2; ++ai)
; #pragma unroll
;                     for (int m = 0; m < 4; ++m) {
;                         const int row = row0 + ai * 128 + m * 16, bb = row >> 13, ss = row & 8191;
; #pragma unroll
;                         for (int bj = 0; bj < 2; ++bj) {
;                             const int col = col0 + bj * 128;
;                             bf16_t* p = sbv + ((size_t)(bb * 1024 + col)) * 8192 + ss;
;                             const f32x4 a = acc[ai][bj][m][0], b = acc[ai][bj][m][1];
; #pragma unroll
;                             for (int j = 0; j < 4; ++j) { p[(size_t)j * 8192] = (bf16_t)f2bf(a[j]); p[(size_t)(4 + j) * 8192] = (bf16_t)f2bf(b[j]); }
;                         }
;                     }
;                 return;
.Ldry_p1vt_c6:
	v_bfe_u32 v40, v43, 16, 1
	v_add3_u32 v40, v43, v40, s21
	global_store_short_d16_hi v[58:59], v40, off offset:32
	v_bfe_u32 v40, v32, 16, 1
	v_add3_u32 v32, v32, v40, s21
	global_store_short_d16_hi v[64:65], v32, off offset:32
	v_bfe_u32 v32, v24, 16, 1
	v_add3_u32 v24, v24, v32, s21
	global_store_short_d16_hi v[66:67], v24, off offset:32
	v_bfe_u32 v24, v33, 16, 1
	v_add3_u32 v24, v33, v24, s21
	global_store_short_d16_hi v[52:53], v24, off offset:32
	v_bfe_u32 v24, v25, 16, 1
	v_add3_u32 v24, v25, v24, s21
	global_store_short_d16_hi v[44:45], v24, off offset:32
	v_bfe_u32 v24, v34, 16, 1
	v_add3_u32 v24, v34, v24, s21
	global_store_short_d16_hi v[76:77], v24, off offset:32
	v_bfe_u32 v24, v26, 16, 1
	v_add3_u32 v24, v26, v24, s21
	global_store_short_d16_hi v[78:79], v24, off offset:32
	v_bfe_u32 v24, v35, 16, 1
	v_add3_u32 v24, v35, v24, s21
	global_store_short_d16_hi v[54:55], v24, off offset:32
	v_bfe_u32 v24, v27, 16, 1
	v_add3_u32 v24, v27, v24, s21
	global_store_short_d16_hi v[46:47], v24, off offset:32
	v_bfe_u32 v24, v36, 16, 1
	v_add3_u32 v24, v36, v24, s21
	global_store_short_d16_hi v[68:69], v24, off offset:64
	v_bfe_u32 v24, v28, 16, 1
	v_add3_u32 v24, v28, v24, s21
	global_store_short_d16_hi v[70:71], v24, off offset:64
	v_bfe_u32 v24, v37, 16, 1
	v_add3_u32 v24, v37, v24, s21
	global_store_short_d16_hi v[60:61], v24, off offset:64
	v_bfe_u32 v24, v29, 16, 1
	v_add3_u32 v24, v29, v24, s21
	global_store_short_d16_hi v[56:57], v24, off offset:64
	v_bfe_u32 v24, v38, 16, 1
	v_add3_u32 v24, v38, v24, s21
	global_store_short_d16_hi v[72:73], v24, off offset:64
	v_bfe_u32 v24, v30, 16, 1
	v_add3_u32 v24, v30, v24, s21
	global_store_short_d16_hi v[74:75], v24, off offset:64
	v_bfe_u32 v24, v39, 16, 1
	v_add3_u32 v24, v39, v24, s21
	global_store_short_d16_hi v[62:63], v24, off offset:64
	v_bfe_u32 v24, v31, 16, 1
	v_add3_u32 v24, v31, v24, s21
	global_store_short_d16_hi v[58:59], v24, off offset:64
	v_bfe_u32 v24, v16, 16, 1
	v_add3_u32 v16, v16, v24, s21
	global_store_short_d16_hi v[64:65], v16, off offset:64
	v_bfe_u32 v16, v8, 16, 1
	v_add3_u32 v8, v8, v16, s21
	global_store_short_d16_hi v[66:67], v8, off offset:64
	v_bfe_u32 v8, v17, 16, 1
	v_add3_u32 v8, v17, v8, s21
	global_store_short_d16_hi v[52:53], v8, off offset:64
	v_bfe_u32 v8, v9, 16, 1
	v_add3_u32 v8, v9, v8, s21
	s_cbranch_execz .Ldry_p1vt_real
.Ldry_p1vt_c7:
	global_store_short_d16_hi v[44:45], v8, off offset:64
	v_bfe_u32 v8, v18, 16, 1
	v_add3_u32 v8, v18, v8, s21
	global_store_short_d16_hi v[76:77], v8, off offset:64
	v_bfe_u32 v8, v10, 16, 1
	v_add3_u32 v8, v10, v8, s21
	global_store_short_d16_hi v[78:79], v8, off offset:64
	v_bfe_u32 v8, v19, 16, 1
	v_add3_u32 v8, v19, v8, s21
	global_store_short_d16_hi v[54:55], v8, off offset:64
	v_bfe_u32 v8, v11, 16, 1
	v_add3_u32 v8, v11, v8, s21
	global_store_short_d16_hi v[46:47], v8, off offset:64
	v_bfe_u32 v8, v20, 16, 1
	v_add3_u32 v8, v20, v8, s21
	global_store_short_d16_hi v[68:69], v8, off offset:96
	v_bfe_u32 v8, v12, 16, 1
	v_add3_u32 v8, v12, v8, s21
	global_store_short_d16_hi v[70:71], v8, off offset:96
	v_bfe_u32 v8, v21, 16, 1
	v_add3_u32 v8, v21, v8, s21
	global_store_short_d16_hi v[60:61], v8, off offset:96
	v_bfe_u32 v8, v13, 16, 1
	v_add3_u32 v8, v13, v8, s21
	global_store_short_d16_hi v[56:57], v8, off offset:96
	v_bfe_u32 v8, v22, 16, 1
	v_add3_u32 v8, v22, v8, s21
	global_store_short_d16_hi v[72:73], v8, off offset:96
	v_bfe_u32 v8, v14, 16, 1
	v_add3_u32 v8, v14, v8, s21
	global_store_short_d16_hi v[74:75], v8, off offset:96
	v_bfe_u32 v8, v23, 16, 1
	v_add3_u32 v8, v23, v8, s21
	global_store_short_d16_hi v[62:63], v8, off offset:96
	v_bfe_u32 v8, v15, 16, 1
	v_add3_u32 v8, v15, v8, s21
	global_store_short_d16_hi v[58:59], v8, off offset:96
	v_bfe_u32 v8, v4, 16, 1
	v_add3_u32 v4, v4, v8, s21
	global_store_short_d16_hi v[64:65], v4, off offset:96
	v_bfe_u32 v4, v0, 16, 1
	v_add3_u32 v0, v0, v4, s21
	global_store_short_d16_hi v[66:67], v0, off offset:96
	v_bfe_u32 v0, v5, 16, 1
	v_add3_u32 v0, v5, v0, s21
	global_store_short_d16_hi v[52:53], v0, off offset:96
	v_bfe_u32 v0, v1, 16, 1
	v_add3_u32 v0, v1, v0, s21
	global_store_short_d16_hi v[44:45], v0, off offset:96
	v_bfe_u32 v0, v6, 16, 1
	v_add3_u32 v0, v6, v0, s21
	global_store_short_d16_hi v[76:77], v0, off offset:96
	v_bfe_u32 v0, v2, 16, 1
	v_add3_u32 v0, v2, v0, s21
	global_store_short_d16_hi v[78:79], v0, off offset:96
	v_bfe_u32 v0, v7, 16, 1
	v_add3_u32 v0, v7, v0, s21
	global_store_short_d16_hi v[54:55], v0, off offset:96
	v_bfe_u32 v0, v3, 16, 1
	v_add3_u32 v0, v3, v0, s21
	global_store_short_d16_hi v[46:47], v0, off offset:96
	s_andn2_b64 vcc, exec, s[6:7]
	s_cbranch_execz .Ldry_p1vt_real
	s_mov_b64 s[4:5], -1
	s_cbranch_vccnz .LBB0_87
	s_branch .LBB0_147

; __device__ __forceinline__ unsigned cvt_pk_bf16(float lo, float hi) { f32x2_t v = {lo, hi}; bf16x2_t b = __builtin_convertvector(v, bf16x2_t); return __builtin_bit_cast(unsigned, b); }
; __device__ __forceinline__ float siluf_(float v) { return v * sigmoidf_(v); }
;     __device__ __forceinline__ void operator()(const f32x4 (&acc)[2][2][4][2], const pg8::Unit& u, int wr, int wc, int fr, int fq) const {
;     ...
;             bf16_t* base = seg == 0 ? sbq : seg == 1 ? sbk : seg == 2 ? sbv : seg == 4 ? hgq : hgi;
;             const float sc = seg == 0 ? 0.08838834764831845f : 1.f; const bool act = seg == 4;
; #pragma unroll
;             for (int ai = 0; ai < 2; ++ai)
; #pragma unroll
;                 for (int m = 0; m < 4; ++m)
; #pragma unroll
;                     for (int bj = 0; bj < 2; ++bj) {
;                         f32x4 a = acc[ai][bj][m][0], b = acc[ai][bj][m][1];
;                         if (act) {
; #pragma unroll
;                             for (int j = 0; j < 4; ++j) { a[j] = siluf_(a[j]); b[j] = siluf_(b[j]); } }
;                         a = a * sc; b = b * sc;
;                         u32x4 w; w.x = cvt_pk_bf16(a[0], a[1]); w.y = cvt_pk_bf16(a[2], a[3]); w.z = cvt_pk_bf16(b[0], b[1]); w.w = cvt_pk_bf16(b[2], b[3]);
;                         *(u32x4*)(base + (size_t)(row0 + ai * 128 + m * 16) * 1024 + col0 + bj * 128) = w;
.LBB0_113:
	s_mov_b64 s[100:101], s[4:5]
	v_readfirstlane_b32 s98, v200
	s_nop 0
	s_lshr_b32 s98, s98, 6
	s_cmp_eq_u32 s98, 0
	s_cbranch_scc1 .Ldry_p1gen_real
	s_mov_b64 exec, 0
	s_cmp_eq_u32 s98, 1
	s_cbranch_scc1 .Ldry_p1gen_c1
	s_cmp_eq_u32 s98, 2
	s_cbranch_scc1 .Ldry_p1gen_c2
	s_cmp_eq_u32 s98, 3
	s_cbranch_scc1 .Ldry_p1gen_c3
	s_cmp_eq_u32 s98, 4
	s_cbranch_scc1 .Ldry_p1gen_c4
	s_cmp_eq_u32 s98, 5
	s_cbranch_scc1 .Ldry_p1gen_c5
	s_cmp_eq_u32 s98, 6
	s_cbranch_scc1 .Ldry_p1gen_c6
	s_branch .Ldry_p1gen_c7
.Ldry_p1gen_real:
	s_mov_b64 exec, -1
	s_mov_b64 s[4:5], s[100:101]
	s_cmp_eq_u32 s29, 4
	v_mov_b64_e32 v[130:131], v[126:127]
	v_mov_b64_e32 v[134:135], v[122:123]
	s_cselect_b64 s[36:37], -1, 0
	s_cmp_lg_u32 s29, 4
	v_mov_b64_e32 v[128:129], v[124:125]
	v_mov_b64_e32 v[132:133], v[120:121]
	s_cbranch_scc1 .LBB0_115
	v_mul_f32_e32 v129, 0xbfb8aa3b, v120
	v_mul_f32_e32 v130, 0xbfb8aa3b, v125
	v_exp_f32_e32 v129, v129
	v_exp_f32_e32 v130, v130
	v_mul_f32_e32 v131, 0xbfb8aa3b, v126
	v_mul_f32_e32 v133, 0xbfb8aa3b, v122
	v_add_f32_e32 v129, 1.0, v129
	v_rcp_f32_e32 v132, v129
	v_add_f32_e32 v129, 1.0, v130
	v_mul_f32_e32 v130, 0xbfb8aa3b, v121
	v_exp_f32_e32 v130, v130
	v_exp_f32_e32 v131, v131
	v_exp_f32_e32 v133, v133
	v_mul_f32_e32 v128, 0xbfb8aa3b, v124
	v_add_f32_e32 v144, 1.0, v130
	v_add_f32_e32 v130, 1.0, v131
	v_add_f32_e32 v131, 1.0, v133
	v_mul_f32_e32 v133, 0xbfb8aa3b, v127
	v_mul_f32_e32 v134, 0xbfb8aa3b, v123
	v_exp_f32_e32 v128, v128
	v_exp_f32_e32 v133, v133
	v_exp_f32_e32 v135, v134
	v_rcp_f32_e32 v134, v131
	v_add_f32_e32 v128, 1.0, v128
	v_add_f32_e32 v131, 1.0, v133
	v_add_f32_e32 v133, 1.0, v135
	v_rcp_f32_e32 v128, v128
	v_rcp_f32_e32 v129, v129
	v_rcp_f32_e32 v130, v130
	v_rcp_f32_e32 v131, v131
	v_rcp_f32_e32 v135, v133
	v_rcp_f32_e32 v133, v144
	v_pk_mul_f32 v[128:129], v[124:125], v[128:129]
	v_pk_mul_f32 v[130:131], v[126:127], v[130:131]
	v_pk_mul_f32 v[134:135], v[122:123], v[134:135]
	v_pk_mul_f32 v[132:133], v[120:121], v[132:133]

; __device__ __forceinline__ unsigned cvt_pk_bf16(float lo, float hi) { f32x2_t v = {lo, hi}; bf16x2_t b = __builtin_convertvector(v, bf16x2_t); return __builtin_bit_cast(unsigned, b); }
; __device__ __forceinline__ float siluf_(float v) { return v * sigmoidf_(v); }
;     __device__ __forceinline__ void operator()(const f32x4 (&acc)[2][2][4][2], const pg8::Unit& u, int wr, int wc, int fr, int fq) const {
;     ...
;             for (int ai = 0; ai < 2; ++ai)
; #pragma unroll
;                 for (int m = 0; m < 4; ++m)
; #pragma unroll
;                     for (int bj = 0; bj < 2; ++bj) {
;                         f32x4 a = acc[ai][bj][m][0], b = acc[ai][bj][m][1];
;                         if (act) {
; #pragma unroll
;                             for (int j = 0; j < 4; ++j) { a[j] = siluf_(a[j]); b[j] = siluf_(b[j]); } }
;                         a = a * sc; b = b * sc;
;                         u32x4 w; w.x = cvt_pk_bf16(a[0], a[1]); w.y = cvt_pk_bf16(a[2], a[3]); w.z = cvt_pk_bf16(b[0], b[1]); w.w = cvt_pk_bf16(b[2], b[3]);
;                         *(u32x4*)(base + (size_t)(row0 + ai * 128 + m * 16) * 1024 + col0 + bj * 128) = w;
.LBB0_117:
	s_mov_b32 s39, s38
	s_mov_b32 s36, s38
	s_mov_b32 s37, s38
	v_pk_mul_f32 v[130:131], s[36:37], v[130:131]
	v_pk_mul_f32 v[128:129], s[38:39], v[128:129]
	v_pk_mul_f32 v[134:135], s[36:37], v[134:135]
	v_pk_mul_f32 v[132:133], s[38:39], v[132:133]
	v_cvt_pk_bf16_f32 v128, v128, v129
	s_cbranch_execz .Ldry_p1gen_real
.Ldry_p1gen_c1:
	v_cvt_pk_bf16_f32 v129, v130, v131
	v_cvt_pk_bf16_f32 v130, v132, v133
	v_cvt_pk_bf16_f32 v131, v134, v135
	global_store_dwordx4 v[158:159], v[128:131], off offset:256
	v_mov_b64_e32 v[134:135], v[106:107]
	s_and_b64 vcc, exec, s[4:5]
	v_mov_b64_e32 v[130:131], v[114:115]
	v_mov_b64_e32 v[128:129], v[112:113]
	v_mov_b64_e32 v[132:133], v[104:105]
	s_cbranch_vccnz .LBB0_119
	v_mul_f32_e32 v129, 0xbfb8aa3b, v104
	v_mul_f32_e32 v130, 0xbfb8aa3b, v113
	v_exp_f32_e32 v129, v129
	v_exp_f32_e32 v130, v130
	v_mul_f32_e32 v131, 0xbfb8aa3b, v114
	v_mul_f32_e32 v133, 0xbfb8aa3b, v106
	v_add_f32_e32 v129, 1.0, v129
	v_rcp_f32_e32 v132, v129
	v_add_f32_e32 v129, 1.0, v130
	v_mul_f32_e32 v130, 0xbfb8aa3b, v105
	v_exp_f32_e32 v130, v130
	v_exp_f32_e32 v131, v131
	v_exp_f32_e32 v133, v133
	v_mul_f32_e32 v128, 0xbfb8aa3b, v112
	v_add_f32_e32 v144, 1.0, v130
	v_add_f32_e32 v130, 1.0, v131
	v_add_f32_e32 v131, 1.0, v133
	v_mul_f32_e32 v133, 0xbfb8aa3b, v115
	v_mul_f32_e32 v134, 0xbfb8aa3b, v107
	v_exp_f32_e32 v128, v128
	v_exp_f32_e32 v133, v133
	v_exp_f32_e32 v135, v134
	v_rcp_f32_e32 v134, v131
	v_add_f32_e32 v128, 1.0, v128
	v_add_f32_e32 v131, 1.0, v133
	v_add_f32_e32 v133, 1.0, v135
	v_rcp_f32_e32 v128, v128
	v_rcp_f32_e32 v129, v129
	v_rcp_f32_e32 v130, v130
	v_rcp_f32_e32 v131, v131
	v_rcp_f32_e32 v135, v133
	v_rcp_f32_e32 v133, v144
	v_pk_mul_f32 v[128:129], v[112:113], v[128:129]
	v_pk_mul_f32 v[130:131], v[114:115], v[130:131]
	v_pk_mul_f32 v[134:135], v[106:107], v[134:135]
	v_pk_mul_f32 v[132:133], v[104:105], v[132:133]

; __device__ __forceinline__ unsigned cvt_pk_bf16(float lo, float hi) { f32x2_t v = {lo, hi}; bf16x2_t b = __builtin_convertvector(v, bf16x2_t); return __builtin_bit_cast(unsigned, b); }
; __device__ __forceinline__ float siluf_(float v) { return v * sigmoidf_(v); }
;     __device__ __forceinline__ void operator()(const f32x4 (&acc)[2][2][4][2], const pg8::Unit& u, int wr, int wc, int fr, int fq) const {
;     ...
;             for (int ai = 0; ai < 2; ++ai)
; #pragma unroll
;                 for (int m = 0; m < 4; ++m)
; #pragma unroll
;                     for (int bj = 0; bj < 2; ++bj) {
;                         f32x4 a = acc[ai][bj][m][0], b = acc[ai][bj][m][1];
;                         if (act) {
; #pragma unroll
;                             for (int j = 0; j < 4; ++j) { a[j] = siluf_(a[j]); b[j] = siluf_(b[j]); } }
;                         a = a * sc; b = b * sc;
;                         u32x4 w; w.x = cvt_pk_bf16(a[0], a[1]); w.y = cvt_pk_bf16(a[2], a[3]); w.z = cvt_pk_bf16(b[0], b[1]); w.w = cvt_pk_bf16(b[2], b[3]);
;                         *(u32x4*)(base + (size_t)(row0 + ai * 128 + m * 16) * 1024 + col0 + bj * 128) = w;
.LBB0_121:
	s_mov_b32 s36, s38
	s_mov_b32 s37, s38
	v_pk_mul_f32 v[130:131], s[36:37], v[130:131]
	v_pk_mul_f32 v[128:129], s[38:39], v[128:129]
	v_pk_mul_f32 v[134:135], s[36:37], v[134:135]
	v_pk_mul_f32 v[132:133], s[38:39], v[132:133]
	v_cvt_pk_bf16_f32 v128, v128, v129
	v_cvt_pk_bf16_f32 v129, v130, v131
	v_cvt_pk_bf16_f32 v130, v132, v133
	s_cbranch_execz .Ldry_p1gen_real
.Ldry_p1gen_c2:
	v_cvt_pk_bf16_f32 v131, v134, v135
	global_store_dwordx4 v[158:159], v[128:131], off offset:256
	v_mov_b64_e32 v[134:135], v[94:95]
	s_and_b64 vcc, exec, s[4:5]
	v_mov_b64_e32 v[130:131], v[102:103]
	v_mov_b64_e32 v[128:129], v[100:101]
	v_mov_b64_e32 v[132:133], v[92:93]
	s_cbranch_vccnz .LBB0_123
	v_mul_f32_e32 v129, 0xbfb8aa3b, v92
	v_mul_f32_e32 v130, 0xbfb8aa3b, v101
	v_exp_f32_e32 v129, v129
	v_exp_f32_e32 v130, v130
	v_mul_f32_e32 v131, 0xbfb8aa3b, v102
	v_mul_f32_e32 v133, 0xbfb8aa3b, v94
	v_add_f32_e32 v129, 1.0, v129
	v_rcp_f32_e32 v132, v129
	v_add_f32_e32 v129, 1.0, v130
	v_mul_f32_e32 v130, 0xbfb8aa3b, v93
	v_exp_f32_e32 v130, v130
	v_exp_f32_e32 v131, v131
	v_exp_f32_e32 v133, v133
	v_mul_f32_e32 v128, 0xbfb8aa3b, v100
	v_add_f32_e32 v144, 1.0, v130
	v_add_f32_e32 v130, 1.0, v131
	v_add_f32_e32 v131, 1.0, v133
	v_mul_f32_e32 v133, 0xbfb8aa3b, v103
	v_mul_f32_e32 v134, 0xbfb8aa3b, v95
	v_exp_f32_e32 v128, v128
	v_exp_f32_e32 v133, v133
	v_exp_f32_e32 v135, v134
	v_rcp_f32_e32 v134, v131
	v_add_f32_e32 v128, 1.0, v128
	v_add_f32_e32 v131, 1.0, v133
	v_add_f32_e32 v133, 1.0, v135
	v_rcp_f32_e32 v128, v128
	v_rcp_f32_e32 v129, v129
	v_rcp_f32_e32 v130, v130
	v_rcp_f32_e32 v131, v131
	v_rcp_f32_e32 v135, v133
	v_rcp_f32_e32 v133, v144
	v_pk_mul_f32 v[128:129], v[100:101], v[128:129]
	v_pk_mul_f32 v[130:131], v[102:103], v[130:131]
	v_pk_mul_f32 v[134:135], v[94:95], v[134:135]
	v_pk_mul_f32 v[132:133], v[92:93], v[132:133]

; __device__ __forceinline__ unsigned cvt_pk_bf16(float lo, float hi) { f32x2_t v = {lo, hi}; bf16x2_t b = __builtin_convertvector(v, bf16x2_t); return __builtin_bit_cast(unsigned, b); }
; __device__ __forceinline__ float siluf_(float v) { return v * sigmoidf_(v); }
;     __device__ __forceinline__ void operator()(const f32x4 (&acc)[2][2][4][2], const pg8::Unit& u, int wr, int wc, int fr, int fq) const {
;     ...
;             for (int ai = 0; ai < 2; ++ai)
; #pragma unroll
;                 for (int m = 0; m < 4; ++m)
; #pragma unroll
;                     for (int bj = 0; bj < 2; ++bj) {
;                         f32x4 a = acc[ai][bj][m][0], b = acc[ai][bj][m][1];
;                         if (act) {
; #pragma unroll
;                             for (int j = 0; j < 4; ++j) { a[j] = siluf_(a[j]); b[j] = siluf_(b[j]); } }
;                         a = a * sc; b = b * sc;
;                         u32x4 w; w.x = cvt_pk_bf16(a[0], a[1]); w.y = cvt_pk_bf16(a[2], a[3]); w.z = cvt_pk_bf16(b[0], b[1]); w.w = cvt_pk_bf16(b[2], b[3]);
;                         *(u32x4*)(base + (size_t)(row0 + ai * 128 + m * 16) * 1024 + col0 + bj * 128) = w;
.LBB0_125:
	s_mov_b32 s36, s38
	s_mov_b32 s37, s38
	v_pk_mul_f32 v[130:131], s[36:37], v[130:131]
	v_pk_mul_f32 v[128:129], s[38:39], v[128:129]
	v_pk_mul_f32 v[134:135], s[36:37], v[134:135]
	v_pk_mul_f32 v[132:133], s[38:39], v[132:133]
	v_cvt_pk_bf16_f32 v128, v128, v129
	v_cvt_pk_bf16_f32 v129, v130, v131
	v_cvt_pk_bf16_f32 v130, v132, v133
	v_cvt_pk_bf16_f32 v131, v134, v135
	s_cbranch_execz .Ldry_p1gen_real
.Ldry_p1gen_c3:
	global_store_dwordx4 v[158:159], v[128:131], off offset:256
	v_mov_b64_e32 v[134:135], v[78:79]
	s_and_b64 vcc, exec, s[4:5]
	v_mov_b64_e32 v[130:131], v[86:87]
	v_mov_b64_e32 v[128:129], v[84:85]
	v_mov_b64_e32 v[132:133], v[76:77]
	s_cbranch_vccnz .LBB0_127
	v_mul_f32_e32 v129, 0xbfb8aa3b, v76
	v_mul_f32_e32 v130, 0xbfb8aa3b, v85
	v_exp_f32_e32 v129, v129
	v_exp_f32_e32 v130, v130
	v_mul_f32_e32 v131, 0xbfb8aa3b, v86
	v_mul_f32_e32 v133, 0xbfb8aa3b, v78
	v_add_f32_e32 v129, 1.0, v129
	v_rcp_f32_e32 v132, v129
	v_add_f32_e32 v129, 1.0, v130
	v_mul_f32_e32 v130, 0xbfb8aa3b, v77
	v_exp_f32_e32 v130, v130
	v_exp_f32_e32 v131, v131
	v_exp_f32_e32 v133, v133
	v_mul_f32_e32 v128, 0xbfb8aa3b, v84
	v_add_f32_e32 v144, 1.0, v130
	v_add_f32_e32 v130, 1.0, v131
	v_add_f32_e32 v131, 1.0, v133
	v_mul_f32_e32 v133, 0xbfb8aa3b, v87
	v_mul_f32_e32 v134, 0xbfb8aa3b, v79
	v_exp_f32_e32 v128, v128
	v_exp_f32_e32 v133, v133
	v_exp_f32_e32 v135, v134
	v_rcp_f32_e32 v134, v131
	v_add_f32_e32 v128, 1.0, v128
	v_add_f32_e32 v131, 1.0, v133
	v_add_f32_e32 v133, 1.0, v135
	v_rcp_f32_e32 v128, v128
	v_rcp_f32_e32 v129, v129
	v_rcp_f32_e32 v130, v130
	v_rcp_f32_e32 v131, v131
	v_rcp_f32_e32 v135, v133
	v_rcp_f32_e32 v133, v144
	v_pk_mul_f32 v[128:129], v[84:85], v[128:129]
	v_pk_mul_f32 v[130:131], v[86:87], v[130:131]
	v_pk_mul_f32 v[134:135], v[78:79], v[134:135]
	v_pk_mul_f32 v[132:133], v[76:77], v[132:133]

; __device__ __forceinline__ unsigned cvt_pk_bf16(float lo, float hi) { f32x2_t v = {lo, hi}; bf16x2_t b = __builtin_convertvector(v, bf16x2_t); return __builtin_bit_cast(unsigned, b); }
; __device__ __forceinline__ float siluf_(float v) { return v * sigmoidf_(v); }
;     __device__ __forceinline__ void operator()(const f32x4 (&acc)[2][2][4][2], const pg8::Unit& u, int wr, int wc, int fr, int fq) const {
;     ...
;             for (int ai = 0; ai < 2; ++ai)
; #pragma unroll
;                 for (int m = 0; m < 4; ++m)
; #pragma unroll
;                     for (int bj = 0; bj < 2; ++bj) {
;                         f32x4 a = acc[ai][bj][m][0], b = acc[ai][bj][m][1];
;                         if (act) {
; #pragma unroll
;                             for (int j = 0; j < 4; ++j) { a[j] = siluf_(a[j]); b[j] = siluf_(b[j]); } }
;                         a = a * sc; b = b * sc;
;                         u32x4 w; w.x = cvt_pk_bf16(a[0], a[1]); w.y = cvt_pk_bf16(a[2], a[3]); w.z = cvt_pk_bf16(b[0], b[1]); w.w = cvt_pk_bf16(b[2], b[3]);
;                         *(u32x4*)(base + (size_t)(row0 + ai * 128 + m * 16) * 1024 + col0 + bj * 128) = w;
.LBB0_129:
	s_mov_b32 s36, s38
	s_mov_b32 s37, s38
	v_pk_mul_f32 v[130:131], s[36:37], v[130:131]
	v_pk_mul_f32 v[128:129], s[38:39], v[128:129]
	v_pk_mul_f32 v[134:135], s[36:37], v[134:135]
	v_pk_mul_f32 v[132:133], s[38:39], v[132:133]
	v_cvt_pk_bf16_f32 v128, v128, v129
	v_cvt_pk_bf16_f32 v129, v130, v131
	v_cvt_pk_bf16_f32 v130, v132, v133
	v_cvt_pk_bf16_f32 v131, v134, v135
	global_store_dwordx4 v[158:159], v[128:131], off offset:256
	v_mov_b64_e32 v[134:135], v[58:59]
	s_cbranch_execz .Ldry_p1gen_real
.Ldry_p1gen_c4:
	s_and_b64 vcc, exec, s[4:5]
	v_mov_b64_e32 v[130:131], v[62:63]
	v_mov_b64_e32 v[128:129], v[60:61]
	v_mov_b64_e32 v[132:133], v[56:57]
	s_cbranch_vccnz .LBB0_131
	v_mul_f32_e32 v129, 0xbfb8aa3b, v56
	v_mul_f32_e32 v130, 0xbfb8aa3b, v61
	v_exp_f32_e32 v129, v129
	v_exp_f32_e32 v130, v130
	v_mul_f32_e32 v131, 0xbfb8aa3b, v62
	v_mul_f32_e32 v133, 0xbfb8aa3b, v58
	v_add_f32_e32 v129, 1.0, v129
	v_rcp_f32_e32 v132, v129
	v_add_f32_e32 v129, 1.0, v130
	v_mul_f32_e32 v130, 0xbfb8aa3b, v57
	v_exp_f32_e32 v130, v130
	v_exp_f32_e32 v131, v131
	v_exp_f32_e32 v133, v133
	v_mul_f32_e32 v128, 0xbfb8aa3b, v60
	v_add_f32_e32 v144, 1.0, v130
	v_add_f32_e32 v130, 1.0, v131
	v_add_f32_e32 v131, 1.0, v133
	v_mul_f32_e32 v133, 0xbfb8aa3b, v63
	v_mul_f32_e32 v134, 0xbfb8aa3b, v59
	v_exp_f32_e32 v128, v128
	v_exp_f32_e32 v133, v133
	v_exp_f32_e32 v135, v134
	v_rcp_f32_e32 v134, v131
	v_add_f32_e32 v128, 1.0, v128
	v_add_f32_e32 v131, 1.0, v133
	v_add_f32_e32 v133, 1.0, v135
	v_rcp_f32_e32 v128, v128
	v_rcp_f32_e32 v129, v129
	v_rcp_f32_e32 v130, v130
	v_rcp_f32_e32 v131, v131
	v_rcp_f32_e32 v135, v133
	v_rcp_f32_e32 v133, v144
	v_pk_mul_f32 v[128:129], v[60:61], v[128:129]
	v_pk_mul_f32 v[130:131], v[62:63], v[130:131]
	v_pk_mul_f32 v[134:135], v[58:59], v[134:135]
	v_pk_mul_f32 v[132:133], v[56:57], v[132:133]

; __device__ __forceinline__ unsigned cvt_pk_bf16(float lo, float hi) { f32x2_t v = {lo, hi}; bf16x2_t b = __builtin_convertvector(v, bf16x2_t); return __builtin_bit_cast(unsigned, b); }
; __device__ __forceinline__ float siluf_(float v) { return v * sigmoidf_(v); }
;     __device__ __forceinline__ void operator()(const f32x4 (&acc)[2][2][4][2], const pg8::Unit& u, int wr, int wc, int fr, int fq) const {
;     ...
;             for (int ai = 0; ai < 2; ++ai)
; #pragma unroll
;                 for (int m = 0; m < 4; ++m)
; #pragma unroll
;                     for (int bj = 0; bj < 2; ++bj) {
;                         f32x4 a = acc[ai][bj][m][0], b = acc[ai][bj][m][1];
;                         if (act) {
; #pragma unroll
;                             for (int j = 0; j < 4; ++j) { a[j] = siluf_(a[j]); b[j] = siluf_(b[j]); } }
;                         a = a * sc; b = b * sc;
;                         u32x4 w; w.x = cvt_pk_bf16(a[0], a[1]); w.y = cvt_pk_bf16(a[2], a[3]); w.z = cvt_pk_bf16(b[0], b[1]); w.w = cvt_pk_bf16(b[2], b[3]);
;                         *(u32x4*)(base + (size_t)(row0 + ai * 128 + m * 16) * 1024 + col0 + bj * 128) = w;
.LBB0_133:
	s_mov_b32 s36, s38
	s_mov_b32 s37, s38
	v_pk_mul_f32 v[130:131], s[36:37], v[130:131]
	v_pk_mul_f32 v[128:129], s[38:39], v[128:129]
	v_pk_mul_f32 v[134:135], s[36:37], v[134:135]
	v_pk_mul_f32 v[132:133], s[38:39], v[132:133]
	v_lshl_add_u64 v[158:159], v[158:159], 0, s[54:55]
	v_cvt_pk_bf16_f32 v128, v128, v129
	v_cvt_pk_bf16_f32 v129, v130, v131
	v_cvt_pk_bf16_f32 v130, v132, v133
	v_cvt_pk_bf16_f32 v131, v134, v135
	global_store_dwordx4 v[158:159], v[128:131], off offset:256
	v_mov_b64_e32 v[134:135], v[42:43]
	s_cbranch_execz .Ldry_p1gen_real
.Ldry_p1gen_c5:
	s_and_b64 vcc, exec, s[4:5]
	v_mov_b64_e32 v[130:131], v[50:51]
	v_mov_b64_e32 v[128:129], v[48:49]
	v_mov_b64_e32 v[132:133], v[40:41]
	s_cbranch_vccnz .LBB0_135
	v_mul_f32_e32 v129, 0xbfb8aa3b, v40
	v_mul_f32_e32 v130, 0xbfb8aa3b, v49
	v_exp_f32_e32 v129, v129
	v_exp_f32_e32 v130, v130
	v_mul_f32_e32 v131, 0xbfb8aa3b, v50
	v_mul_f32_e32 v133, 0xbfb8aa3b, v42
	v_add_f32_e32 v129, 1.0, v129
	v_rcp_f32_e32 v132, v129
	v_add_f32_e32 v129, 1.0, v130
	v_mul_f32_e32 v130, 0xbfb8aa3b, v41
	v_exp_f32_e32 v130, v130
	v_exp_f32_e32 v131, v131
	v_exp_f32_e32 v133, v133
	v_mul_f32_e32 v128, 0xbfb8aa3b, v48
	v_add_f32_e32 v144, 1.0, v130
	v_add_f32_e32 v130, 1.0, v131
	v_add_f32_e32 v131, 1.0, v133
	v_mul_f32_e32 v133, 0xbfb8aa3b, v51
	v_mul_f32_e32 v134, 0xbfb8aa3b, v43
	v_exp_f32_e32 v128, v128
	v_exp_f32_e32 v133, v133
	v_exp_f32_e32 v135, v134
	v_rcp_f32_e32 v134, v131
	v_add_f32_e32 v128, 1.0, v128
	v_add_f32_e32 v131, 1.0, v133
	v_add_f32_e32 v133, 1.0, v135
	v_rcp_f32_e32 v128, v128
	v_rcp_f32_e32 v129, v129
	v_rcp_f32_e32 v130, v130
	v_rcp_f32_e32 v131, v131
	v_rcp_f32_e32 v135, v133
	v_rcp_f32_e32 v133, v144
	v_pk_mul_f32 v[128:129], v[48:49], v[128:129]
	v_pk_mul_f32 v[130:131], v[50:51], v[130:131]
	v_pk_mul_f32 v[134:135], v[42:43], v[134:135]
	v_pk_mul_f32 v[132:133], v[40:41], v[132:133]

; __device__ __forceinline__ unsigned cvt_pk_bf16(float lo, float hi) { f32x2_t v = {lo, hi}; bf16x2_t b = __builtin_convertvector(v, bf16x2_t); return __builtin_bit_cast(unsigned, b); }
; __device__ __forceinline__ float siluf_(float v) { return v * sigmoidf_(v); }
;     __device__ __forceinline__ void operator()(const f32x4 (&acc)[2][2][4][2], const pg8::Unit& u, int wr, int wc, int fr, int fq) const {
;     ...
;             for (int ai = 0; ai < 2; ++ai)
; #pragma unroll
;                 for (int m = 0; m < 4; ++m)
; #pragma unroll
;                     for (int bj = 0; bj < 2; ++bj) {
;                         f32x4 a = acc[ai][bj][m][0], b = acc[ai][bj][m][1];
;                         if (act) {
; #pragma unroll
;                             for (int j = 0; j < 4; ++j) { a[j] = siluf_(a[j]); b[j] = siluf_(b[j]); } }
;                         a = a * sc; b = b * sc;
;                         u32x4 w; w.x = cvt_pk_bf16(a[0], a[1]); w.y = cvt_pk_bf16(a[2], a[3]); w.z = cvt_pk_bf16(b[0], b[1]); w.w = cvt_pk_bf16(b[2], b[3]);
;                         *(u32x4*)(base + (size_t)(row0 + ai * 128 + m * 16) * 1024 + col0 + bj * 128) = w;
.LBB0_137:
	s_mov_b32 s36, s38
	s_mov_b32 s37, s38
	v_pk_mul_f32 v[130:131], s[36:37], v[130:131]
	v_pk_mul_f32 v[128:129], s[38:39], v[128:129]
	v_pk_mul_f32 v[134:135], s[36:37], v[134:135]
	v_pk_mul_f32 v[132:133], s[38:39], v[132:133]
	v_lshl_add_u64 v[158:159], v[158:159], 0, s[56:57]
	v_cvt_pk_bf16_f32 v128, v128, v129
	v_cvt_pk_bf16_f32 v129, v130, v131
	v_cvt_pk_bf16_f32 v130, v132, v133
	v_cvt_pk_bf16_f32 v131, v134, v135
	global_store_dwordx4 v[158:159], v[128:131], off offset:256
	s_cbranch_execz .Ldry_p1gen_real
.Ldry_p1gen_c6:
	v_mov_b64_e32 v[134:135], v[30:31]
	s_and_b64 vcc, exec, s[4:5]
	v_mov_b64_e32 v[130:131], v[38:39]
	v_mov_b64_e32 v[128:129], v[36:37]
	v_mov_b64_e32 v[132:133], v[28:29]
	s_cbranch_vccnz .LBB0_139
	v_mul_f32_e32 v129, 0xbfb8aa3b, v28
	v_mul_f32_e32 v130, 0xbfb8aa3b, v37
	v_exp_f32_e32 v129, v129
	v_exp_f32_e32 v130, v130
	v_mul_f32_e32 v131, 0xbfb8aa3b, v38
	v_mul_f32_e32 v133, 0xbfb8aa3b, v30
	v_add_f32_e32 v129, 1.0, v129
	v_rcp_f32_e32 v132, v129
	v_add_f32_e32 v129, 1.0, v130
	v_mul_f32_e32 v130, 0xbfb8aa3b, v29
	v_exp_f32_e32 v130, v130
	v_exp_f32_e32 v131, v131
	v_exp_f32_e32 v133, v133
	v_mul_f32_e32 v128, 0xbfb8aa3b, v36
	v_add_f32_e32 v144, 1.0, v130
	v_add_f32_e32 v130, 1.0, v131
	v_add_f32_e32 v131, 1.0, v133
	v_mul_f32_e32 v133, 0xbfb8aa3b, v39
	v_mul_f32_e32 v134, 0xbfb8aa3b, v31
	v_exp_f32_e32 v128, v128
	v_exp_f32_e32 v133, v133
	v_exp_f32_e32 v135, v134
	v_rcp_f32_e32 v134, v131
	v_add_f32_e32 v128, 1.0, v128
	v_add_f32_e32 v131, 1.0, v133
	v_add_f32_e32 v133, 1.0, v135
	v_rcp_f32_e32 v128, v128
	v_rcp_f32_e32 v129, v129
	v_rcp_f32_e32 v130, v130
	v_rcp_f32_e32 v131, v131
	v_rcp_f32_e32 v135, v133
	v_rcp_f32_e32 v133, v144
	v_pk_mul_f32 v[128:129], v[36:37], v[128:129]
	v_pk_mul_f32 v[130:131], v[38:39], v[130:131]
	v_pk_mul_f32 v[134:135], v[30:31], v[134:135]
	v_pk_mul_f32 v[132:133], v[28:29], v[132:133]

; __device__ __forceinline__ unsigned cvt_pk_bf16(float lo, float hi) { f32x2_t v = {lo, hi}; bf16x2_t b = __builtin_convertvector(v, bf16x2_t); return __builtin_bit_cast(unsigned, b); }
; __device__ __forceinline__ float siluf_(float v) { return v * sigmoidf_(v); }
;     __device__ __forceinline__ void operator()(const f32x4 (&acc)[2][2][4][2], const pg8::Unit& u, int wr, int wc, int fr, int fq) const {
;     ...
;             for (int ai = 0; ai < 2; ++ai)
; #pragma unroll
;                 for (int m = 0; m < 4; ++m)
; #pragma unroll
;                     for (int bj = 0; bj < 2; ++bj) {
;                         f32x4 a = acc[ai][bj][m][0], b = acc[ai][bj][m][1];
;                         if (act) {
; #pragma unroll
;                             for (int j = 0; j < 4; ++j) { a[j] = siluf_(a[j]); b[j] = siluf_(b[j]); } }
;                         a = a * sc; b = b * sc;
;                         u32x4 w; w.x = cvt_pk_bf16(a[0], a[1]); w.y = cvt_pk_bf16(a[2], a[3]); w.z = cvt_pk_bf16(b[0], b[1]); w.w = cvt_pk_bf16(b[2], b[3]);
;                         *(u32x4*)(base + (size_t)(row0 + ai * 128 + m * 16) * 1024 + col0 + bj * 128) = w;
.LBB0_141:
	s_mov_b32 s36, s38
	s_mov_b32 s37, s38
	v_pk_mul_f32 v[130:131], s[36:37], v[130:131]
	v_pk_mul_f32 v[128:129], s[38:39], v[128:129]
	v_pk_mul_f32 v[134:135], s[36:37], v[134:135]
	v_pk_mul_f32 v[132:133], s[38:39], v[132:133]
	v_lshl_add_u64 v[158:159], v[158:159], 0, s[22:23]
	v_cvt_pk_bf16_f32 v128, v128, v129
	v_cvt_pk_bf16_f32 v129, v130, v131
	v_cvt_pk_bf16_f32 v130, v132, v133
	v_cvt_pk_bf16_f32 v131, v134, v135
	global_store_dwordx4 v[158:159], v[128:131], off offset:256
	s_cbranch_execz .Ldry_p1gen_real
.Ldry_p1gen_c7:
	v_mov_b64_e32 v[134:135], v[14:15]
	s_and_b64 vcc, exec, s[4:5]
	v_mov_b64_e32 v[130:131], v[22:23]
	v_mov_b64_e32 v[128:129], v[20:21]
	v_mov_b64_e32 v[132:133], v[12:13]
	s_cbranch_vccnz .LBB0_143
	v_mul_f32_e32 v129, 0xbfb8aa3b, v12
	v_mul_f32_e32 v130, 0xbfb8aa3b, v21
	v_exp_f32_e32 v129, v129
	v_exp_f32_e32 v130, v130
	v_mul_f32_e32 v131, 0xbfb8aa3b, v22
	v_mul_f32_e32 v133, 0xbfb8aa3b, v14
	v_add_f32_e32 v129, 1.0, v129
	v_rcp_f32_e32 v132, v129
	v_add_f32_e32 v129, 1.0, v130
	v_mul_f32_e32 v130, 0xbfb8aa3b, v13
	v_exp_f32_e32 v130, v130
	v_exp_f32_e32 v131, v131
	v_exp_f32_e32 v133, v133
	v_mul_f32_e32 v128, 0xbfb8aa3b, v20
	v_add_f32_e32 v144, 1.0, v130
	v_add_f32_e32 v130, 1.0, v131
	v_add_f32_e32 v131, 1.0, v133
	v_mul_f32_e32 v133, 0xbfb8aa3b, v23
	v_mul_f32_e32 v134, 0xbfb8aa3b, v15
	v_exp_f32_e32 v128, v128
	v_exp_f32_e32 v133, v133
	v_exp_f32_e32 v135, v134
	v_rcp_f32_e32 v134, v131
	v_add_f32_e32 v128, 1.0, v128
	v_add_f32_e32 v131, 1.0, v133
	v_add_f32_e32 v133, 1.0, v135
	v_rcp_f32_e32 v128, v128
	v_rcp_f32_e32 v129, v129
	v_rcp_f32_e32 v130, v130
	v_rcp_f32_e32 v131, v131
	v_rcp_f32_e32 v135, v133
	v_rcp_f32_e32 v133, v144
	v_pk_mul_f32 v[128:129], v[20:21], v[128:129]
	v_pk_mul_f32 v[130:131], v[22:23], v[130:131]
	v_pk_mul_f32 v[134:135], v[14:15], v[134:135]
	v_pk_mul_f32 v[132:133], v[12:13], v[132:133]

; template <class Epi, class Sched, bool ALIGN_EPI = false, bool SP2 = false>
; __device__ __forceinline__ void gemm_phase(LAS unsigned char* lds, const Gemm g, const Sched& S, const Epi& E) {
;     ...
;         if constexpr (!Epi::AFTER_DRAIN) { E(acc, cur, wr, wc, fr, fq); S.done(cur); }
;         if (!has_next) break;
.LBB0_146:
	s_cbranch_execz .Ldry_p1gen_real
	s_andn2_b64 vcc, exec, s[6:7]
	s_mov_b64 s[4:5], -1
	s_cbranch_vccnz .LBB0_87
